# mix2: gated-norm loops read their 4 operand loads ahead of the stores (on top of the unit-start load batching)
# speedup vs baseline: 1.0047x; 1.0047x over previous
.LBB0_98:
	v_or_b32_e32 v6, s0, v8
	v_ashrrev_i32_e32 v7, 31, v6
	v_lshl_add_u64 v[4:5], v[6:7], 2, s[38:39]
	global_load_dwordx4 v[144:147], v[4:5], off
	global_load_dwordx4 v[148:151], v[4:5], off offset:64
	global_load_dwordx4 v[152:155], v[4:5], off offset:128
	global_load_dwordx4 v[156:159], v[4:5], off offset:192
	v_lshl_add_u32 v14, v6, 1, v81
	v_add_u32_e32 v20, 0x4000, v14
	ds_read2_b64 v[14:17], v20 offset0:64 offset1:68
	s_mov_b32 s0, 64
	s_and_b64 vcc, exec, s[4:5]
	s_mov_b64 s[4:5], 0
	s_waitcnt lgkmcnt(0)
	v_cvt_f32_f16_e32 v18, v14
	v_cvt_f32_f16_sdwa v19, v14 dst_sel:DWORD dst_unused:UNUSED_PAD src0_sel:WORD_1
	v_cvt_f32_f16_e32 v14, v15
	v_cvt_f32_f16_sdwa v15, v15 dst_sel:DWORD dst_unused:UNUSED_PAD src0_sel:WORD_1
	v_pk_mul_f32 v[18:19], v[0:1], v[18:19]
	v_pk_mul_f32 v[14:15], v[0:1], v[14:15]
	s_waitcnt vmcnt(3)
	v_pk_mul_f32 v[10:11], v[144:145], v[18:19]
	v_pk_mul_f32 v[12:13], v[146:147], v[14:15]
	v_cvt_pk_f16_f32 v10, v10, v11
	v_cvt_pk_f16_f32 v11, v12, v13
	v_lshl_add_u64 v[12:13], v[6:7], 1, v[2:3]
	global_store_dwordx2 v[12:13], v[10:11], off
	v_cvt_f32_f16_e32 v18, v16
	v_cvt_f32_f16_sdwa v19, v16 dst_sel:DWORD dst_unused:UNUSED_PAD src0_sel:WORD_1
	v_cvt_f32_f16_e32 v16, v17
	v_cvt_f32_f16_sdwa v17, v17 dst_sel:DWORD dst_unused:UNUSED_PAD src0_sel:WORD_1
	v_or_b32_e32 v14, 16, v6
	v_pk_mul_f32 v[18:19], v[0:1], v[18:19]
	v_ashrrev_i32_e32 v15, 31, v14
	v_pk_mul_f32 v[16:17], v[0:1], v[16:17]
	s_waitcnt vmcnt(3)
	v_pk_mul_f32 v[10:11], v[148:149], v[18:19]
	v_pk_mul_f32 v[12:13], v[150:151], v[16:17]
	v_cvt_pk_f16_f32 v10, v10, v11
	v_cvt_pk_f16_f32 v11, v12, v13
	v_lshl_add_u64 v[12:13], v[14:15], 1, v[2:3]
	global_store_dwordx2 v[12:13], v[10:11], off
	ds_read2_b64 v[10:13], v20 offset0:72 offset1:76
	v_or_b32_e32 v18, 32, v6
	v_ashrrev_i32_e32 v19, 31, v18
	s_waitcnt lgkmcnt(0)
	v_cvt_f32_f16_e32 v20, v10
	v_cvt_f32_f16_sdwa v21, v10 dst_sel:DWORD dst_unused:UNUSED_PAD src0_sel:WORD_1
	v_pk_mul_f32 v[20:21], v[0:1], v[20:21]
	s_waitcnt vmcnt(3)
	v_pk_mul_f32 v[14:15], v[152:153], v[20:21]
	s_nop 0
	v_cvt_pk_f16_f32 v10, v14, v15
	v_cvt_f32_f16_e32 v14, v11
	v_cvt_f32_f16_sdwa v15, v11 dst_sel:DWORD dst_unused:UNUSED_PAD src0_sel:WORD_1
	v_pk_mul_f32 v[14:15], v[0:1], v[14:15]
	s_nop 0
	v_pk_mul_f32 v[14:15], v[154:155], v[14:15]
	s_nop 0
	v_cvt_pk_f16_f32 v11, v14, v15
	v_lshl_add_u64 v[14:15], v[18:19], 1, v[2:3]
	global_store_dwordx2 v[14:15], v[10:11], off
	v_or_b32_e32 v10, 48, v6
	v_cvt_f32_f16_e32 v14, v12
	v_cvt_f32_f16_sdwa v15, v12 dst_sel:DWORD dst_unused:UNUSED_PAD src0_sel:WORD_1
	v_cvt_f32_f16_e32 v12, v13
	v_cvt_f32_f16_sdwa v13, v13 dst_sel:DWORD dst_unused:UNUSED_PAD src0_sel:WORD_1
	v_ashrrev_i32_e32 v11, 31, v10
	v_pk_mul_f32 v[14:15], v[0:1], v[14:15]
	v_pk_mul_f32 v[12:13], v[0:1], v[12:13]
	s_waitcnt vmcnt(3)
	v_pk_mul_f32 v[4:5], v[156:157], v[14:15]
	v_pk_mul_f32 v[6:7], v[158:159], v[12:13]
	v_cvt_pk_f16_f32 v4, v4, v5
	v_cvt_pk_f16_f32 v5, v6, v7
	v_lshl_add_u64 v[6:7], v[10:11], 1, v[2:3]
	global_store_dwordx2 v[6:7], v[4:5], off
	s_cbranch_vccnz .LBB0_98
	ds_read2_b32 v[0:1], v9 offset0:16 offset1:48
	s_mov_b32 s0, 0x800000
	s_mov_b64 s[4:5], 0x47ffb00
	s_waitcnt lgkmcnt(0)
	v_add_f32_e32 v2, v0, v1
	ds_read2_b32 v[0:1], v9 offset0:80 offset1:112
	s_waitcnt lgkmcnt(0)
	v_add_f32_e32 v0, v2, v0
	v_add_f32_e32 v0, v0, v1
	v_fmamk_f32 v0, v0, 0x3b000000, v170
	v_cmp_gt_f32_e32 vcc, s0, v0
	v_mul_f32_e32 v1, 0x4b800000, v0
	v_lshlrev_b64 v[2:3], 12, v[72:73]
	v_cndmask_b32_e32 v0, v0, v1, vcc
	v_rsq_f32_e32 v0, v0
	v_lshl_add_u64 v[2:3], s[20:21], 0, v[2:3]
	v_lshl_add_u64 v[2:3], v[2:3], 0, s[4:5]
	s_mov_b32 s0, 0
	v_mul_f32_e32 v1, 0x45800000, v0
	v_cndmask_b32_e32 v0, v0, v1, vcc
	v_mov_b32_e32 v1, v0
	s_mov_b64 s[4:5], -1
.LBB0_100:
	v_or_b32_e32 v6, s0, v8
	v_ashrrev_i32_e32 v7, 31, v6
	v_lshl_add_u64 v[4:5], v[6:7], 2, s[38:39]
	global_load_dwordx4 v[144:147], v[4:5], off
	global_load_dwordx4 v[148:151], v[4:5], off offset:64
	global_load_dwordx4 v[152:155], v[4:5], off offset:128
	global_load_dwordx4 v[156:159], v[4:5], off offset:192
	v_lshl_add_u32 v9, v6, 1, v79
	v_add_u32_e32 v9, 0x4000, v9
	ds_read2_b64 v[14:17], v9 offset0:64 offset1:68
	s_mov_b32 s0, 64
	s_and_b64 vcc, exec, s[4:5]
	s_mov_b64 s[4:5], 0
	s_waitcnt lgkmcnt(0)
	v_cvt_f32_f16_e32 v18, v14
	v_cvt_f32_f16_sdwa v19, v14 dst_sel:DWORD dst_unused:UNUSED_PAD src0_sel:WORD_1
	v_cvt_f32_f16_e32 v14, v15
	v_cvt_f32_f16_sdwa v15, v15 dst_sel:DWORD dst_unused:UNUSED_PAD src0_sel:WORD_1
	v_pk_mul_f32 v[18:19], v[0:1], v[18:19]
	v_pk_mul_f32 v[14:15], v[0:1], v[14:15]
	s_waitcnt vmcnt(3)
	v_pk_mul_f32 v[10:11], v[144:145], v[18:19]
	v_pk_mul_f32 v[12:13], v[146:147], v[14:15]
	v_cvt_pk_f16_f32 v10, v10, v11
	v_cvt_pk_f16_f32 v11, v12, v13
	v_lshl_add_u64 v[12:13], v[6:7], 1, v[2:3]
	global_store_dwordx2 v[12:13], v[10:11], off
	v_cvt_f32_f16_e32 v18, v16
	v_cvt_f32_f16_sdwa v19, v16 dst_sel:DWORD dst_unused:UNUSED_PAD src0_sel:WORD_1
	v_cvt_f32_f16_e32 v16, v17
	v_cvt_f32_f16_sdwa v17, v17 dst_sel:DWORD dst_unused:UNUSED_PAD src0_sel:WORD_1
	v_or_b32_e32 v14, 16, v6
	v_pk_mul_f32 v[18:19], v[0:1], v[18:19]
	v_ashrrev_i32_e32 v15, 31, v14
	v_pk_mul_f32 v[16:17], v[0:1], v[16:17]
	s_waitcnt vmcnt(3)
	v_pk_mul_f32 v[10:11], v[148:149], v[18:19]
	v_pk_mul_f32 v[12:13], v[150:151], v[16:17]
	v_cvt_pk_f16_f32 v10, v10, v11
	v_cvt_pk_f16_f32 v11, v12, v13
	v_lshl_add_u64 v[12:13], v[14:15], 1, v[2:3]
	global_store_dwordx2 v[12:13], v[10:11], off
	ds_read2_b64 v[10:13], v9 offset0:72 offset1:76
	v_or_b32_e32 v18, 32, v6
	v_ashrrev_i32_e32 v19, 31, v18
	s_waitcnt lgkmcnt(0)
	v_cvt_f32_f16_e32 v20, v10
	v_cvt_f32_f16_sdwa v21, v10 dst_sel:DWORD dst_unused:UNUSED_PAD src0_sel:WORD_1
	v_pk_mul_f32 v[20:21], v[0:1], v[20:21]
	s_waitcnt vmcnt(3)
	v_pk_mul_f32 v[14:15], v[152:153], v[20:21]
	s_nop 0
	v_cvt_pk_f16_f32 v10, v14, v15
	v_cvt_f32_f16_e32 v14, v11
	v_cvt_f32_f16_sdwa v15, v11 dst_sel:DWORD dst_unused:UNUSED_PAD src0_sel:WORD_1
	v_pk_mul_f32 v[14:15], v[0:1], v[14:15]
	s_nop 0
	v_pk_mul_f32 v[14:15], v[154:155], v[14:15]
	s_nop 0
	v_cvt_pk_f16_f32 v11, v14, v15
	v_lshl_add_u64 v[14:15], v[18:19], 1, v[2:3]
	global_store_dwordx2 v[14:15], v[10:11], off
	v_or_b32_e32 v10, 48, v6
	v_cvt_f32_f16_e32 v14, v12
	v_cvt_f32_f16_sdwa v15, v12 dst_sel:DWORD dst_unused:UNUSED_PAD src0_sel:WORD_1
	v_cvt_f32_f16_e32 v12, v13
	v_cvt_f32_f16_sdwa v13, v13 dst_sel:DWORD dst_unused:UNUSED_PAD src0_sel:WORD_1
	v_ashrrev_i32_e32 v11, 31, v10
	v_pk_mul_f32 v[14:15], v[0:1], v[14:15]
	v_pk_mul_f32 v[12:13], v[0:1], v[12:13]
	s_waitcnt vmcnt(3)
	v_pk_mul_f32 v[4:5], v[156:157], v[14:15]
	v_pk_mul_f32 v[6:7], v[158:159], v[12:13]
	v_cvt_pk_f16_f32 v4, v4, v5
	v_cvt_pk_f16_f32 v5, v6, v7
	v_lshl_add_u64 v[6:7], v[10:11], 1, v[2:3]
	global_store_dwordx2 v[6:7], v[4:5], off
	s_cbranch_vccnz .LBB0_100

.LBB0_111:
	v_or_b32_e32 v6, s0, v8
	v_ashrrev_i32_e32 v7, 31, v6
	v_lshl_add_u64 v[4:5], v[6:7], 2, s[38:39]
	global_load_dwordx4 v[144:147], v[4:5], off
	global_load_dwordx4 v[148:151], v[4:5], off offset:64
	global_load_dwordx4 v[152:155], v[4:5], off offset:128
	global_load_dwordx4 v[156:159], v[4:5], off offset:192
	v_lshl_add_u32 v14, v6, 1, v93
	v_add_u32_e32 v20, 0x4000, v14
	ds_read2_b64 v[14:17], v20 offset0:64 offset1:68
	s_mov_b32 s0, 64
	s_and_b64 vcc, exec, s[4:5]
	s_mov_b64 s[4:5], 0
	s_waitcnt lgkmcnt(0)
	v_cvt_f32_f16_e32 v18, v14
	v_cvt_f32_f16_sdwa v19, v14 dst_sel:DWORD dst_unused:UNUSED_PAD src0_sel:WORD_1
	v_cvt_f32_f16_e32 v14, v15
	v_cvt_f32_f16_sdwa v15, v15 dst_sel:DWORD dst_unused:UNUSED_PAD src0_sel:WORD_1
	v_pk_mul_f32 v[18:19], v[0:1], v[18:19]
	v_pk_mul_f32 v[14:15], v[0:1], v[14:15]
	s_waitcnt vmcnt(3)
	v_pk_mul_f32 v[10:11], v[144:145], v[18:19]
	v_pk_mul_f32 v[12:13], v[146:147], v[14:15]
	v_cvt_pk_f16_f32 v10, v10, v11
	v_cvt_pk_f16_f32 v11, v12, v13
	v_lshl_add_u64 v[12:13], v[6:7], 1, v[2:3]
	global_store_dwordx2 v[12:13], v[10:11], off
	v_cvt_f32_f16_e32 v18, v16
	v_cvt_f32_f16_sdwa v19, v16 dst_sel:DWORD dst_unused:UNUSED_PAD src0_sel:WORD_1
	v_cvt_f32_f16_e32 v16, v17
	v_cvt_f32_f16_sdwa v17, v17 dst_sel:DWORD dst_unused:UNUSED_PAD src0_sel:WORD_1
	v_or_b32_e32 v14, 16, v6
	v_pk_mul_f32 v[18:19], v[0:1], v[18:19]
	v_ashrrev_i32_e32 v15, 31, v14
	v_pk_mul_f32 v[16:17], v[0:1], v[16:17]
	s_waitcnt vmcnt(3)
	v_pk_mul_f32 v[10:11], v[148:149], v[18:19]
	v_pk_mul_f32 v[12:13], v[150:151], v[16:17]
	v_cvt_pk_f16_f32 v10, v10, v11
	v_cvt_pk_f16_f32 v11, v12, v13
	v_lshl_add_u64 v[12:13], v[14:15], 1, v[2:3]
	global_store_dwordx2 v[12:13], v[10:11], off
	ds_read2_b64 v[10:13], v20 offset0:72 offset1:76
	v_or_b32_e32 v18, 32, v6
	v_ashrrev_i32_e32 v19, 31, v18
	s_waitcnt lgkmcnt(0)
	v_cvt_f32_f16_e32 v20, v10
	v_cvt_f32_f16_sdwa v21, v10 dst_sel:DWORD dst_unused:UNUSED_PAD src0_sel:WORD_1
	v_pk_mul_f32 v[20:21], v[0:1], v[20:21]
	s_waitcnt vmcnt(3)
	v_pk_mul_f32 v[14:15], v[152:153], v[20:21]
	s_nop 0
	v_cvt_pk_f16_f32 v10, v14, v15
	v_cvt_f32_f16_e32 v14, v11
	v_cvt_f32_f16_sdwa v15, v11 dst_sel:DWORD dst_unused:UNUSED_PAD src0_sel:WORD_1
	v_pk_mul_f32 v[14:15], v[0:1], v[14:15]
	s_nop 0
	v_pk_mul_f32 v[14:15], v[154:155], v[14:15]
	s_nop 0
	v_cvt_pk_f16_f32 v11, v14, v15
	v_lshl_add_u64 v[14:15], v[18:19], 1, v[2:3]
	global_store_dwordx2 v[14:15], v[10:11], off
	v_or_b32_e32 v10, 48, v6
	v_cvt_f32_f16_e32 v14, v12
	v_cvt_f32_f16_sdwa v15, v12 dst_sel:DWORD dst_unused:UNUSED_PAD src0_sel:WORD_1
	v_cvt_f32_f16_e32 v12, v13
	v_cvt_f32_f16_sdwa v13, v13 dst_sel:DWORD dst_unused:UNUSED_PAD src0_sel:WORD_1
	v_ashrrev_i32_e32 v11, 31, v10
	v_pk_mul_f32 v[14:15], v[0:1], v[14:15]
	v_pk_mul_f32 v[12:13], v[0:1], v[12:13]
	s_waitcnt vmcnt(3)
	v_pk_mul_f32 v[4:5], v[156:157], v[14:15]
	v_pk_mul_f32 v[6:7], v[158:159], v[12:13]
	v_cvt_pk_f16_f32 v4, v4, v5
	v_cvt_pk_f16_f32 v5, v6, v7
	v_lshl_add_u64 v[6:7], v[10:11], 1, v[2:3]
	global_store_dwordx2 v[6:7], v[4:5], off
	s_cbranch_vccnz .LBB0_111
	ds_read2_b32 v[0:1], v9 offset0:16 offset1:48
	s_mov_b32 s0, 0x800000
	s_mov_b64 s[4:5], 0x47ffb00
	s_waitcnt lgkmcnt(0)
	v_add_f32_e32 v2, v0, v1
	ds_read2_b32 v[0:1], v9 offset0:80 offset1:112
	s_waitcnt lgkmcnt(0)
	v_add_f32_e32 v0, v2, v0
	v_add_f32_e32 v0, v0, v1
	v_fmamk_f32 v0, v0, 0x3b000000, v170
	v_cmp_gt_f32_e32 vcc, s0, v0
	v_mul_f32_e32 v1, 0x4b800000, v0
	v_lshlrev_b64 v[2:3], 12, v[32:33]
	v_cndmask_b32_e32 v0, v0, v1, vcc
	v_rsq_f32_e32 v0, v0
	v_lshl_add_u64 v[2:3], s[20:21], 0, v[2:3]
	v_lshl_add_u64 v[2:3], v[2:3], 0, s[4:5]
	s_mov_b32 s0, 0
	v_mul_f32_e32 v1, 0x45800000, v0
	v_cndmask_b32_e32 v0, v0, v1, vcc
	v_mov_b32_e32 v1, v0
	s_mov_b64 s[4:5], -1
.LBB0_113:
	v_or_b32_e32 v6, s0, v8
	v_cndmask_b32_e64 v4, 0, 1, s[4:5]
	v_ashrrev_i32_e32 v7, 31, v6
	v_cmp_ne_u32_e32 vcc, 1, v4
	v_lshl_add_u64 v[4:5], v[6:7], 2, s[38:39]
	global_load_dwordx4 v[144:147], v[4:5], off
	global_load_dwordx4 v[148:151], v[4:5], off offset:64
	global_load_dwordx4 v[152:155], v[4:5], off offset:128
	global_load_dwordx4 v[156:159], v[4:5], off offset:192
	v_lshl_add_u32 v9, v6, 1, v92
	v_add_u32_e32 v9, 0x4000, v9
	ds_read2_b64 v[14:17], v9 offset0:64 offset1:68
	s_mov_b32 s0, 64
	s_mov_b64 s[4:5], 0
	s_and_b64 vcc, exec, vcc
	s_waitcnt lgkmcnt(0)
	v_cvt_f32_f16_e32 v18, v14
	v_cvt_f32_f16_sdwa v19, v14 dst_sel:DWORD dst_unused:UNUSED_PAD src0_sel:WORD_1
	v_cvt_f32_f16_e32 v14, v15
	v_cvt_f32_f16_sdwa v15, v15 dst_sel:DWORD dst_unused:UNUSED_PAD src0_sel:WORD_1
	v_pk_mul_f32 v[18:19], v[0:1], v[18:19]
	v_pk_mul_f32 v[14:15], v[0:1], v[14:15]
	s_waitcnt vmcnt(3)
	v_pk_mul_f32 v[10:11], v[144:145], v[18:19]
	v_pk_mul_f32 v[12:13], v[146:147], v[14:15]
	v_cvt_pk_f16_f32 v10, v10, v11
	v_cvt_pk_f16_f32 v11, v12, v13
	v_lshl_add_u64 v[12:13], v[6:7], 1, v[2:3]
	global_store_dwordx2 v[12:13], v[10:11], off
	v_cvt_f32_f16_e32 v18, v16
	v_cvt_f32_f16_sdwa v19, v16 dst_sel:DWORD dst_unused:UNUSED_PAD src0_sel:WORD_1
	v_cvt_f32_f16_e32 v16, v17
	v_cvt_f32_f16_sdwa v17, v17 dst_sel:DWORD dst_unused:UNUSED_PAD src0_sel:WORD_1
	v_or_b32_e32 v14, 16, v6
	v_pk_mul_f32 v[18:19], v[0:1], v[18:19]
	v_ashrrev_i32_e32 v15, 31, v14
	v_pk_mul_f32 v[16:17], v[0:1], v[16:17]
	s_waitcnt vmcnt(3)
	v_pk_mul_f32 v[10:11], v[148:149], v[18:19]
	v_pk_mul_f32 v[12:13], v[150:151], v[16:17]
	v_cvt_pk_f16_f32 v10, v10, v11
	v_cvt_pk_f16_f32 v11, v12, v13
	v_lshl_add_u64 v[12:13], v[14:15], 1, v[2:3]
	global_store_dwordx2 v[12:13], v[10:11], off
	ds_read2_b64 v[10:13], v9 offset0:72 offset1:76
	v_or_b32_e32 v18, 32, v6
	v_ashrrev_i32_e32 v19, 31, v18
	s_waitcnt lgkmcnt(0)
	v_cvt_f32_f16_e32 v20, v10
	v_cvt_f32_f16_sdwa v21, v10 dst_sel:DWORD dst_unused:UNUSED_PAD src0_sel:WORD_1
	v_pk_mul_f32 v[20:21], v[0:1], v[20:21]
	s_waitcnt vmcnt(3)
	v_pk_mul_f32 v[14:15], v[152:153], v[20:21]
	s_nop 0
	v_cvt_pk_f16_f32 v10, v14, v15
	v_cvt_f32_f16_e32 v14, v11
	v_cvt_f32_f16_sdwa v15, v11 dst_sel:DWORD dst_unused:UNUSED_PAD src0_sel:WORD_1
	v_pk_mul_f32 v[14:15], v[0:1], v[14:15]
	s_nop 0
	v_pk_mul_f32 v[14:15], v[154:155], v[14:15]
	s_nop 0
	v_cvt_pk_f16_f32 v11, v14, v15
	v_lshl_add_u64 v[14:15], v[18:19], 1, v[2:3]
	global_store_dwordx2 v[14:15], v[10:11], off
	v_or_b32_e32 v10, 48, v6
	v_cvt_f32_f16_e32 v14, v12
	v_cvt_f32_f16_sdwa v15, v12 dst_sel:DWORD dst_unused:UNUSED_PAD src0_sel:WORD_1
	v_cvt_f32_f16_e32 v12, v13
	v_cvt_f32_f16_sdwa v13, v13 dst_sel:DWORD dst_unused:UNUSED_PAD src0_sel:WORD_1
	v_ashrrev_i32_e32 v11, 31, v10
	v_pk_mul_f32 v[14:15], v[0:1], v[14:15]
	v_pk_mul_f32 v[12:13], v[0:1], v[12:13]
	s_waitcnt vmcnt(3)
	v_pk_mul_f32 v[4:5], v[156:157], v[14:15]
	v_pk_mul_f32 v[6:7], v[158:159], v[12:13]
	v_cvt_pk_f16_f32 v4, v4, v5
	v_cvt_pk_f16_f32 v5, v6, v7
	v_lshl_add_u64 v[6:7], v[10:11], 1, v[2:3]
	global_store_dwordx2 v[6:7], v[4:5], off
	s_cbranch_vccz .LBB0_113
	s_branch .LBB0_39
